# attention: per-lane partial row sums carried across tiles, cross-lane sum reduction done once per sub-unit
# baseline (speedup 1.0000x reference)
; DI unsigned pk2(float lo, float hi) { const f32x2 v = {lo, hi}; const bf16x2_t b = __builtin_convertvector(v, bf16x2_t); return __builtin_bit_cast(unsigned, b); }
; DI float xr16_sum(float x) { float a = x, b = x; XR_SWAP("v_permlane16_swap_b32", a, b); return a + b; }
; DI float xr32_sum(float x) { float a = x, b = x; XR_SWAP("v_permlane32_swap_b32", a, b); return a + b; }
; DI void u_attn2(Frame& F, int h, int qb, int sp, int ntile) {
;     ...
;                 float ps = 0.f; float p[16];
; #pragma unroll
;                 for (int kb = 0; kb < 4; ++kb)
; #pragma unroll
;                     for (int r = 0; r < 4; ++r) { p[kb * 4 + r] = __builtin_amdgcn_exp2f(s[kb][qq][r] - mn); ps += p[kb * 4 + r]; }
;                 ps = xr32_sum(xr16_sum(ps));
;                 lrun[qq] = lrun[qq] * alpha + ps;
; if (__builtin_amdgcn_ballot_w64(alpha != 1.0f) != 0ull) {
; #pragma unroll
;                     for (int db = 0; db < 8; ++db) o[db][qq] = o[db][qq] * alpha; }
; #pragma unroll
;                 for (int s2 = 0; s2 < 2; ++s2) { u32x4 pw; pw.x = pk2(p[8 * s2], p[8 * s2 + 1]); pw.y = pk2(p[8 * s2 + 2], p[8 * s2 + 3]); pw.z = pk2(p[8 * s2 + 4], p[8 * s2 + 5]); pw.w = pk2(p[8 * s2 + 6], p[8 * s2 + 7]); pf[qq][s2] = __builtin_bit_cast(bf16x8, pw); }
.Latt_r1_A:
	v_exp_f32_e32 v218, v218
	v_exp_f32_e32 v219, v219
	v_exp_f32_e32 v220, v220
	v_exp_f32_e32 v221, v221
	v_exp_f32_e32 v214, v214
	v_exp_f32_e32 v215, v215
	v_exp_f32_e32 v216, v216
	v_exp_f32_e32 v217, v217
	v_exp_f32_e32 v222, v222
	v_exp_f32_e32 v223, v223
	v_exp_f32_e32 v224, v224
	v_exp_f32_e32 v225, v225
	v_exp_f32_e32 v154, v154
	v_exp_f32_e32 v155, v155
	v_exp_f32_e32 v156, v156
	v_exp_f32_e32 v157, v157
	v_exp_f32_e32 v150, v150
	v_exp_f32_e32 v151, v151
	v_exp_f32_e32 v152, v152
	v_exp_f32_e32 v153, v153
	v_exp_f32_e32 v146, v146
	v_exp_f32_e32 v147, v147
	v_exp_f32_e32 v148, v148
	v_exp_f32_e32 v149, v149
	v_exp_f32_e32 v142, v142
	v_exp_f32_e32 v143, v143
	v_exp_f32_e32 v144, v144
	v_exp_f32_e32 v145, v145
	v_exp_f32_e32 v138, v138
	v_exp_f32_e32 v139, v139
	v_exp_f32_e32 v140, v140
	v_exp_f32_e32 v141, v141
	v_add_f32_e32 v198, v218, v219
	v_add_f32_e32 v199, v220, v221
	v_add_f32_e32 v200, v214, v215
	v_add_f32_e32 v201, v216, v217
	v_add_f32_e32 v210, v150, v151
	v_add_f32_e32 v211, v152, v153
	v_add_f32_e32 v212, v146, v147
	v_add_f32_e32 v213, v148, v149
	v_add_f32_e32 v198, v198, v222
	v_add_f32_e32 v199, v199, v223
	v_add_f32_e32 v200, v200, v224
	v_add_f32_e32 v201, v201, v225
	v_add_f32_e32 v210, v210, v142
	v_add_f32_e32 v211, v211, v143
	v_add_f32_e32 v212, v212, v144
	v_add_f32_e32 v213, v213, v145
	v_add_f32_e32 v198, v198, v154
	v_add_f32_e32 v199, v199, v155
	v_add_f32_e32 v200, v200, v156
	v_add_f32_e32 v201, v201, v157
	v_add_f32_e32 v210, v210, v138
	v_add_f32_e32 v211, v211, v139
	v_add_f32_e32 v212, v212, v140
	v_add_f32_e32 v213, v213, v141
	v_add_f32_e32 v198, v198, v199
	v_add_f32_e32 v200, v200, v201
	v_add_f32_e32 v210, v210, v211
	v_add_f32_e32 v212, v212, v213
	v_add_f32_e32 v198, v198, v200
	v_add_f32_e32 v210, v210, v212
	v_fma_f32 v165, v165, v18, v198
	v_fma_f32 v163, v163, v20, v210
	v_mov_b32_e32 v164, v21
	v_mov_b32_e32 v162, v191
	v_cvt_pk_bf16_f32 v198, v218, v219
	v_cvt_pk_bf16_f32 v199, v220, v221
	v_cvt_pk_bf16_f32 v200, v214, v215
	v_cvt_pk_bf16_f32 v201, v216, v217
	v_cvt_pk_bf16_f32 v192, v222, v223
	v_cvt_pk_bf16_f32 v193, v224, v225
	v_cvt_pk_bf16_f32 v194, v154, v155
	v_cvt_pk_bf16_f32 v195, v156, v157
	v_cvt_pk_bf16_f32 v210, v150, v151
	v_cvt_pk_bf16_f32 v211, v152, v153
	v_cvt_pk_bf16_f32 v212, v146, v147
	v_cvt_pk_bf16_f32 v213, v148, v149
	v_cvt_pk_bf16_f32 v142, v142, v143
	v_cvt_pk_bf16_f32 v143, v144, v145
	v_cvt_pk_bf16_f32 v144, v138, v139
	v_cvt_pk_bf16_f32 v145, v140, v141
	s_branch .LBB0_2236

; DI unsigned pk2(float lo, float hi) { const f32x2 v = {lo, hi}; const bf16x2_t b = __builtin_convertvector(v, bf16x2_t); return __builtin_bit_cast(unsigned, b); }
; DI float xr16_sum(float x) { float a = x, b = x; XR_SWAP("v_permlane16_swap_b32", a, b); return a + b; }
; DI float xr32_sum(float x) { float a = x, b = x; XR_SWAP("v_permlane32_swap_b32", a, b); return a + b; }
; DI void u_attn2(Frame& F, int h, int qb, int sp, int ntile) {
;     ...
;                 float ps = 0.f; float p[16];
; #pragma unroll
;                 for (int kb = 0; kb < 4; ++kb)
; #pragma unroll
;                     for (int r = 0; r < 4; ++r) { p[kb * 4 + r] = __builtin_amdgcn_exp2f(s[kb][qq][r] - mn); ps += p[kb * 4 + r]; }
;                 ps = xr32_sum(xr16_sum(ps));
;                 lrun[qq] = lrun[qq] * alpha + ps;
; if (__builtin_amdgcn_ballot_w64(alpha != 1.0f) != 0ull) {
; #pragma unroll
;                     for (int db = 0; db < 8; ++db) o[db][qq] = o[db][qq] * alpha; }
; #pragma unroll
;                 for (int s2 = 0; s2 < 2; ++s2) { u32x4 pw; pw.x = pk2(p[8 * s2], p[8 * s2 + 1]); pw.y = pk2(p[8 * s2 + 2], p[8 * s2 + 3]); pw.z = pk2(p[8 * s2 + 4], p[8 * s2 + 5]); pw.w = pk2(p[8 * s2 + 6], p[8 * s2 + 7]); pf[qq][s2] = __builtin_bit_cast(bf16x8, pw); }
.Latt_r1_B:
	v_exp_f32_e32 v218, v218
	v_exp_f32_e32 v219, v219
	v_exp_f32_e32 v220, v220
	v_exp_f32_e32 v221, v221
	v_exp_f32_e32 v214, v214
	v_exp_f32_e32 v215, v215
	v_exp_f32_e32 v216, v216
	v_exp_f32_e32 v217, v217
	v_exp_f32_e32 v222, v222
	v_exp_f32_e32 v223, v223
	v_exp_f32_e32 v224, v224
	v_exp_f32_e32 v225, v225
	v_exp_f32_e32 v154, v154
	v_exp_f32_e32 v155, v155
	v_exp_f32_e32 v156, v156
	v_exp_f32_e32 v157, v157
	v_exp_f32_e32 v150, v150
	v_exp_f32_e32 v151, v151
	v_exp_f32_e32 v152, v152
	v_exp_f32_e32 v153, v153
	v_exp_f32_e32 v146, v146
	v_exp_f32_e32 v147, v147
	v_exp_f32_e32 v148, v148
	v_exp_f32_e32 v149, v149
	v_exp_f32_e32 v142, v142
	v_exp_f32_e32 v143, v143
	v_exp_f32_e32 v144, v144
	v_exp_f32_e32 v145, v145
	v_exp_f32_e32 v138, v138
	v_exp_f32_e32 v139, v139
	v_exp_f32_e32 v140, v140
	v_exp_f32_e32 v141, v141
	v_add_f32_e32 v198, v218, v219
	v_add_f32_e32 v199, v220, v221
	v_add_f32_e32 v200, v214, v215
	v_add_f32_e32 v201, v216, v217
	v_add_f32_e32 v210, v150, v151
	v_add_f32_e32 v211, v152, v153
	v_add_f32_e32 v212, v146, v147
	v_add_f32_e32 v213, v148, v149
	v_add_f32_e32 v198, v198, v222
	v_add_f32_e32 v199, v199, v223
	v_add_f32_e32 v200, v200, v224
	v_add_f32_e32 v201, v201, v225
	v_add_f32_e32 v210, v210, v142
	v_add_f32_e32 v211, v211, v143
	v_add_f32_e32 v212, v212, v144
	v_add_f32_e32 v213, v213, v145
	v_add_f32_e32 v198, v198, v154
	v_add_f32_e32 v199, v199, v155
	v_add_f32_e32 v200, v200, v156
	v_add_f32_e32 v201, v201, v157
	v_add_f32_e32 v210, v210, v138
	v_add_f32_e32 v211, v211, v139
	v_add_f32_e32 v212, v212, v140
	v_add_f32_e32 v213, v213, v141
	v_add_f32_e32 v198, v198, v199
	v_add_f32_e32 v200, v200, v201
	v_add_f32_e32 v210, v210, v211
	v_add_f32_e32 v212, v212, v213
	v_add_f32_e32 v198, v198, v200
	v_add_f32_e32 v210, v210, v212
	v_fma_f32 v165, v165, v18, v198
	v_fma_f32 v163, v163, v20, v210
	v_mov_b32_e32 v164, v21
	v_mov_b32_e32 v162, v191
	v_cvt_pk_bf16_f32 v198, v218, v219
	v_cvt_pk_bf16_f32 v199, v220, v221
	v_cvt_pk_bf16_f32 v200, v214, v215
	v_cvt_pk_bf16_f32 v201, v216, v217
	v_cvt_pk_bf16_f32 v192, v222, v223
	v_cvt_pk_bf16_f32 v193, v224, v225
	v_cvt_pk_bf16_f32 v194, v154, v155
	v_cvt_pk_bf16_f32 v195, v156, v157
	v_cvt_pk_bf16_f32 v210, v150, v151
	v_cvt_pk_bf16_f32 v211, v152, v153
	v_cvt_pk_bf16_f32 v212, v146, v147
	v_cvt_pk_bf16_f32 v213, v148, v149
	v_cvt_pk_bf16_f32 v142, v142, v143
	v_cvt_pk_bf16_f32 v143, v144, v145
	v_cvt_pk_bf16_f32 v144, v138, v139
	v_cvt_pk_bf16_f32 v145, v140, v141

; #define GAS __attribute__((address_space(1)))
; DI float xr16_sum(float x) { float a = x, b = x; XR_SWAP("v_permlane16_swap_b32", a, b); return a + b; }
; DI float xr32_sum(float x) { float a = x, b = x; XR_SWAP("v_permlane32_swap_b32", a, b); return a + b; }
; DI u32x2 pk4_(const f32x4 v) { u32x2 o; o.x = pk2(v.x, v.y); o.y = pk2(v.z, v.w); return o; }
; DI void u_attn2(Frame& F, int h, int qb, int sp, int ntile) {
;     ...
;                 ps = xr32_sum(xr16_sum(ps));
;                 lrun[qq] = lrun[qq] * alpha + ps;
;     ...
;     const int slot = att_slot(h, qb, sp);
;     bf16* po = (bf16*)(ws + WS_APO) + (size_t)slot * 32768; float* pm = (float*)(ws + WS_APM) + (size_t)slot * 512;
; #pragma unroll
;     for (int db = 0; db < 8; ++db)
; #pragma unroll
;         for (int qq = 0; qq < 2; ++qq) *(GAS u32x2*)(po + (size_t)(w * 32 + qq * 16 + lc) * 128 + db * 16 + 4 * g4) = pk4_(o[db][qq]);
;     if (g4 == 0) {
; #pragma unroll
;         for (int qq = 0; qq < 2; ++qq) { *(GAS f32x2*)(pm + (w * 32 + qq * 16 + lc) * 2) = (f32x2){mrun[qq], lrun[qq]}; } }
.LBB0_2244:
.LBB0_2245:
	s_or_b64 exec, exec, s[30:31]
	v_mov_b32_e32 v18, v165
	v_mov_b32_e32 v20, v163
	s_nop 0
	v_permlane16_swap_b32 v165, v18
	v_permlane16_swap_b32 v163, v20
	s_nop 0
	v_add_f32_e32 v165, v165, v18
	v_add_f32_e32 v163, v163, v20
	v_mov_b32_e32 v18, v165
	v_mov_b32_e32 v20, v163
	s_nop 0
	v_permlane32_swap_b32 v165, v18
	v_permlane32_swap_b32 v163, v20
	s_nop 0
	v_add_f32_e32 v165, v165, v18
	v_add_f32_e32 v163, v163, v20
	v_lshrrev_b32_e32 v2, 2, v177
	v_add_u32_e32 v4, 1, v2
	v_lshlrev_b32_e32 v2, 1, v2
	v_sub_u32_e32 v2, v177, v2
	v_mul_u32_u24_e32 v3, 0x90, v178
	v_mul_i32_i24_e32 v2, v2, v4
	v_add3_u32 v2, v176, v3, v2
	v_ashrrev_i32_e32 v3, 31, v2
	v_lshlrev_b64 v[4:5], 16, v[2:3]
	v_lshl_add_u64 v[8:9], s[22:23], 0, v[4:5]
	v_or_b32_e32 v4, s42, v161
	v_mov_b32_e32 v161, v19
	v_ashrrev_i32_e32 v5, 31, v4
	v_or_b32_e32 v14, 16, v4
	v_lshl_add_u64 v[8:9], v[8:9], 0, v[160:161]
	v_lshlrev_b64 v[12:13], 8, v[4:5]
	v_ashrrev_i32_e32 v15, 31, v14
	v_cvt_pk_bf16_f32 v10, v134, v135
	v_cvt_pk_bf16_f32 v11, v136, v137
	v_lshl_add_u64 v[12:13], v[8:9], 0, v[12:13]
	v_lshlrev_b64 v[14:15], 8, v[14:15]
	global_store_dwordx2 v[12:13], v[10:11], off
	v_cvt_pk_bf16_f32 v10, v118, v119
	v_cvt_pk_bf16_f32 v11, v120, v121
	v_lshl_add_u64 v[8:9], v[8:9], 0, v[14:15]
	global_store_dwordx2 v[8:9], v[10:11], off
	v_cvt_pk_bf16_f32 v10, v106, v107
	v_cvt_pk_bf16_f32 v11, v108, v109
	global_store_dwordx2 v[12:13], v[10:11], off offset:32
	v_cvt_pk_bf16_f32 v10, v102, v103
	v_cvt_pk_bf16_f32 v11, v104, v105
	global_store_dwordx2 v[8:9], v[10:11], off offset:32
	v_cvt_pk_bf16_f32 v10, v98, v99
	v_cvt_pk_bf16_f32 v11, v100, v101
	global_store_dwordx2 v[12:13], v[10:11], off offset:64
	v_cvt_pk_bf16_f32 v10, v94, v95
	v_cvt_pk_bf16_f32 v11, v96, v97
	global_store_dwordx2 v[8:9], v[10:11], off offset:64
	v_cvt_pk_bf16_f32 v10, v90, v91
	v_cvt_pk_bf16_f32 v11, v92, v93
	global_store_dwordx2 v[12:13], v[10:11], off offset:96
	v_cvt_pk_bf16_f32 v10, v86, v87
	v_cvt_pk_bf16_f32 v11, v88, v89
	global_store_dwordx2 v[8:9], v[10:11], off offset:96
	v_cvt_pk_bf16_f32 v10, v82, v83
	v_cvt_pk_bf16_f32 v11, v84, v85
	global_store_dwordx2 v[12:13], v[10:11], off offset:128
	v_cvt_pk_bf16_f32 v10, v78, v79
	v_cvt_pk_bf16_f32 v11, v80, v81
	global_store_dwordx2 v[8:9], v[10:11], off offset:128
	v_cvt_pk_bf16_f32 v10, v70, v71
	v_cvt_pk_bf16_f32 v11, v72, v73
	global_store_dwordx2 v[12:13], v[10:11], off offset:160
	v_cvt_pk_bf16_f32 v10, v74, v75
	v_cvt_pk_bf16_f32 v11, v76, v77
	global_store_dwordx2 v[8:9], v[10:11], off offset:160
	v_cvt_pk_bf16_f32 v10, v66, v67
	v_cvt_pk_bf16_f32 v11, v68, v69
	global_store_dwordx2 v[12:13], v[10:11], off offset:192
	v_cvt_pk_bf16_f32 v10, v58, v59
	v_cvt_pk_bf16_f32 v11, v60, v61
	v_and_b32_e32 v6, 63, v158
	global_store_dwordx2 v[8:9], v[10:11], off offset:192
	v_cvt_pk_bf16_f32 v10, v54, v55
	v_cvt_pk_bf16_f32 v11, v56, v57
	global_store_dwordx2 v[12:13], v[10:11], off offset:224
	v_cvt_pk_bf16_f32 v10, v62, v63
	v_cvt_pk_bf16_f32 v11, v64, v65
	v_cmp_gt_u32_e32 vcc, 16, v6
	global_store_dwordx2 v[8:9], v[10:11], off offset:224
	s_and_saveexec_b64 s[30:31], vcc
	v_readlane_b32 s46, v235, 30
	v_readlane_b32 s47, v235, 31
	s_cbranch_execz .LBB0_2230
	v_lshlrev_b64 v[2:3], 11, v[2:3]
	v_lshlrev_b32_e32 v4, 1, v4
	v_lshl_add_u64 v[2:3], s[26:27], 0, v[2:3]
	v_ashrrev_i32_e32 v5, 31, v4
	v_lshl_add_u64 v[2:3], v[4:5], 2, v[2:3]
	global_store_dwordx2 v[2:3], v[164:165], off
	global_store_dwordx2 v[2:3], v[162:163], off offset:128
	s_branch .LBB0_2230
